# attention main loop: first two P.V MFMAs of each step issued inside the row-max section (matrix pipe idle there) instead of at the head of the exp phase; self-max canonicalisations and the +0 add of t
# speedup vs baseline: 1.0050x; 1.0050x over previous
.LBB0_1547:
	v_add_u32_e32 v0, s8, v221
	ds_read_b64_tr_b16 v[192:193], v0 offset:24576
	ds_read_b64_tr_b16 v[194:195], v0 offset:25088
	s_waitcnt lgkmcnt(9)
	v_mfma_f32_32x32x16_bf16 v[112:127], v[188:191], v[148:151], v[48:63]
	v_add_f32_e32 v2, v80, v81
	v_add_f32_e32 v2, v82, v2
	v_add_f32_e32 v2, v83, v2
	v_add_f32_e32 v2, v84, v2
	v_add_f32_e32 v2, v85, v2
	v_cvt_pk_bf16_f32 v156, v80, v81
	v_cvt_pk_bf16_f32 v157, v82, v83
	ds_read_b64_tr_b16 v[188:189], v0 offset:28672
	ds_read_b64_tr_b16 v[190:191], v0 offset:29184
	s_waitcnt lgkmcnt(10)
	v_mfma_f32_32x32x16_bf16 v[96:111], v[184:187], v[148:151], v[48:63]
	v_add_f32_e32 v2, v86, v2
	v_add_f32_e32 v2, v87, v2
	v_add_f32_e32 v2, v88, v2
	v_add_f32_e32 v2, v89, v2
	v_cvt_pk_bf16_f32 v158, v84, v85
	v_cvt_pk_bf16_f32 v159, v86, v87
	ds_read_b64_tr_b16 v[184:185], v0 offset:25600
	ds_read_b64_tr_b16 v[186:187], v0 offset:26112
	s_waitcnt lgkmcnt(11)
	v_mfma_f32_32x32x16_bf16 v[112:127], v[180:183], v[140:143], v[112:127]
	v_add_f32_e32 v2, v90, v2
	v_add_f32_e32 v2, v91, v2
	v_add_f32_e32 v2, v92, v2
	v_add_f32_e32 v2, v93, v2
	v_cvt_pk_bf16_f32 v152, v88, v89
	v_cvt_pk_bf16_f32 v153, v90, v91
	ds_read_b64_tr_b16 v[84:85], v0 offset:29696
	ds_read_b64_tr_b16 v[86:87], v0 offset:30208
	s_waitcnt lgkmcnt(12)
	v_mfma_f32_32x32x16_bf16 v[96:111], v[176:179], v[140:143], v[96:111]
	v_add_f32_e32 v2, v94, v2
	v_add_f32_e32 v2, v95, v2
	v_add_f32_e32 v2, v64, v2
	v_add_f32_e32 v2, v65, v2
	v_cvt_pk_bf16_f32 v154, v92, v93
	v_cvt_pk_bf16_f32 v155, v94, v95
	ds_read_b64_tr_b16 v[80:81], v0 offset:26624
	ds_read_b64_tr_b16 v[82:83], v0 offset:27136
	s_waitcnt lgkmcnt(13)
	v_mfma_f32_32x32x16_bf16 v[112:127], v[172:175], v[132:135], v[112:127]
	v_add_f32_e32 v2, v66, v2
	v_add_f32_e32 v2, v67, v2
	v_add_f32_e32 v2, v68, v2
	v_add_f32_e32 v2, v69, v2
	v_cvt_pk_bf16_f32 v144, v64, v65
	v_cvt_pk_bf16_f32 v145, v66, v67
	ds_read_b64_tr_b16 v[10:11], v0 offset:30720
	ds_read_b64_tr_b16 v[12:13], v0 offset:31232
	s_waitcnt lgkmcnt(14)
	v_mfma_f32_32x32x16_bf16 v[96:111], v[168:171], v[132:135], v[96:111]
	v_add_f32_e32 v2, v70, v2
	v_add_f32_e32 v2, v71, v2
	v_add_f32_e32 v2, v72, v2
	v_add_f32_e32 v2, v73, v2
	v_cvt_pk_bf16_f32 v146, v68, v69
	v_cvt_pk_bf16_f32 v147, v70, v71
	ds_read_b64_tr_b16 v[6:7], v0 offset:27648
	ds_read_b64_tr_b16 v[8:9], v0 offset:28160
	s_waitcnt lgkmcnt(14)
	v_mfma_f32_32x32x16_bf16 v[112:127], v[164:167], v[128:131], v[112:127]
	v_add_f32_e32 v2, v74, v2
	v_add_f32_e32 v2, v75, v2
	v_add_f32_e32 v2, v76, v2
	v_add_f32_e32 v14, v77, v2
	v_cvt_pk_bf16_f32 v136, v72, v73
	v_cvt_pk_bf16_f32 v137, v74, v75
	ds_read_b64_tr_b16 v[2:3], v0 offset:31744
	ds_read_b64_tr_b16 v[4:5], v0 offset:32256
	v_mfma_f32_32x32x16_bf16 v[96:111], v[160:163], v[128:131], v[96:111]
	v_add_f32_e32 v0, v78, v14
	v_add_f32_e32 v0, v79, v0
	v_cvt_pk_bf16_f32 v138, v76, v77
	v_cvt_pk_bf16_f32 v139, v78, v79
	v_lshl_add_u64 v[14:15], v[202:203], 0, s[26:27]
	s_add_i32 s8, s40, s46
	s_mov_b32 s9, m0
	s_mov_b32 m0, s8
	s_nop 0
	global_load_lds_dwordx4 v[14:15], off
	s_mov_b32 m0, s9
	v_lshl_add_u64 v[14:15], v[200:201], 0, s[26:27]
	s_add_i32 s8, s38, s47
	s_mov_b32 s9, m0
	s_mov_b32 m0, s8
	s_nop 0
	global_load_lds_dwordx4 v[14:15], off
	s_mov_b32 m0, s9
	s_waitcnt lgkmcnt(14)
	v_mfma_f32_32x32x16_bf16 v[32:47], v[156:159], v[192:195], v[32:47]
	v_max_f32_e32 v14, v112, v113
	v_max3_f32 v15, v114, v115, v97
	v_max3_f32 v14, v14, v96, v98
	v_max3_f32 v14, v14, v99, v116
	v_max3_f32 v15, v15, v118, v119
	v_max3_f32 v14, v14, v117, v100
	s_waitcnt lgkmcnt(12)
	v_mfma_f32_32x32x16_bf16 v[16:31], v[156:159], v[188:191], v[16:31]
	v_max3_f32 v15, v15, v102, v103
	v_max3_f32 v14, v14, v101, v120
	v_max3_f32 v15, v15, v122, v123
	v_max3_f32 v14, v14, v121, v104
	v_max3_f32 v15, v15, v106, v107
	v_max3_f32 v14, v14, v105, v124
	v_max3_f32 v15, v15, v126, v127
	v_max3_f32 v64, v14, v125, v108
	v_max3_f32 v15, v15, v110, v111
	v_add_f32_e32 v14, v223, v0
	v_max3_f32 v0, v64, v109, v15
	v_mov_b32_e32 v15, v0
	s_nop 1
	v_permlane32_swap_b32_e32 v0, v15
	v_max_f32_e32 v0, v0, v15
	v_cmp_lt_f32_e32 vcc, s53, v0
	s_cmp_lg_u64 vcc, 0
	s_cselect_b64 s[8:9], -1, 0
	s_cbranch_vccnz .LBB0_1555
.LBB0_1548:
	v_exp_f32_e32 v112, v112
	v_exp_f32_e32 v113, v113
	v_exp_f32_e32 v114, v114
	v_exp_f32_e32 v115, v115
	v_exp_f32_e32 v116, v116
	v_exp_f32_e32 v117, v117
	v_exp_f32_e32 v118, v118
	v_exp_f32_e32 v119, v119
	v_add_u32_e32 v0, s38, v220
	ds_read_b128 v[64:67], v0
	ds_read_b128 v[160:163], v0 offset:512
	s_waitcnt lgkmcnt(12)
	v_mfma_f32_32x32x16_bf16 v[32:47], v[152:155], v[184:187], v[32:47]
	v_exp_f32_e32 v120, v120
	v_exp_f32_e32 v121, v121
	v_exp_f32_e32 v122, v122
	v_exp_f32_e32 v123, v123
	ds_read_b128 v[192:195], v0 offset:2048
	ds_read_b128 v[184:187], v0 offset:2560
	s_waitcnt lgkmcnt(12)
	v_mfma_f32_32x32x16_bf16 v[16:31], v[152:155], v[84:87], v[16:31]
	v_exp_f32_e32 v124, v124
	v_exp_f32_e32 v125, v125
	v_exp_f32_e32 v126, v126
	v_exp_f32_e32 v127, v127
	ds_read_b128 v[188:191], v0 offset:4096
	ds_read_b128 v[176:179], v0 offset:4608
	s_waitcnt lgkmcnt(12)
	v_mfma_f32_32x32x16_bf16 v[32:47], v[144:147], v[80:83], v[32:47]
	v_exp_f32_e32 v96, v96
	v_exp_f32_e32 v97, v97
	v_exp_f32_e32 v98, v98
	v_exp_f32_e32 v99, v99
	ds_read_b128 v[180:183], v0 offset:6144
	ds_read_b128 v[172:175], v0 offset:6656
	s_waitcnt lgkmcnt(12)
	v_mfma_f32_32x32x16_bf16 v[16:31], v[144:147], v[10:13], v[16:31]
	v_exp_f32_e32 v100, v100
	v_exp_f32_e32 v101, v101
	v_exp_f32_e32 v102, v102
	v_exp_f32_e32 v103, v103
	s_waitcnt lgkmcnt(10)
	v_mfma_f32_32x32x16_bf16 v[32:47], v[136:139], v[6:9], v[32:47]
	v_exp_f32_e32 v104, v104
	v_exp_f32_e32 v105, v105
	v_exp_f32_e32 v106, v106
	v_exp_f32_e32 v107, v107
	s_waitcnt lgkmcnt(8)
	v_mfma_f32_32x32x16_bf16 v[16:31], v[136:139], v[2:5], v[16:31]
	v_exp_f32_e32 v108, v108
	v_exp_f32_e32 v109, v109
	v_exp_f32_e32 v110, v110
	v_exp_f32_e32 v111, v111
	s_waitcnt vmcnt(2) lgkmcnt(0)
	s_barrier
	s_andn2_b64 vcc, exec, s[8:9]
	v_add_u32_e32 v0, s48, v222
	s_cbranch_vccnz .LBB0_1550
	s_waitcnt lgkmcnt(0)
	ds_read_b128 v[2:5], v0 offset:49248
	ds_read_b128 v[6:9], v0 offset:49216
	ds_read_b128 v[10:13], v0 offset:49184
	ds_read_b128 v[68:71], v0 offset:49152
	s_waitcnt lgkmcnt(3)
	v_pk_mul_f32 v[44:45], v[44:45], v[2:3]
	s_waitcnt lgkmcnt(2)
	v_pk_mul_f32 v[40:41], v[40:41], v[6:7]
	s_waitcnt lgkmcnt(1)
	v_pk_mul_f32 v[36:37], v[36:37], v[10:11]
	v_pk_mul_f32 v[46:47], v[46:47], v[4:5]
	v_pk_mul_f32 v[42:43], v[42:43], v[8:9]
	v_pk_mul_f32 v[38:39], v[38:39], v[12:13]
	s_waitcnt lgkmcnt(0)
	v_pk_mul_f32 v[34:35], v[34:35], v[70:71]
	v_pk_mul_f32 v[32:33], v[32:33], v[68:69]
	v_pk_mul_f32 v[28:29], v[28:29], v[2:3]
	v_pk_mul_f32 v[24:25], v[24:25], v[6:7]
	v_pk_mul_f32 v[20:21], v[20:21], v[10:11]
	v_pk_mul_f32 v[30:31], v[30:31], v[4:5]
	v_pk_mul_f32 v[26:27], v[26:27], v[8:9]
	v_pk_mul_f32 v[22:23], v[22:23], v[12:13]
	v_pk_mul_f32 v[18:19], v[18:19], v[70:71]
	v_pk_mul_f32 v[16:17], v[16:17], v[68:69]
.LBB0_1550:
	s_add_i32 s8, s38, 0x2000
	s_cmpk_lg_i32 s38, 0x4000
	s_cselect_b32 s13, s8, 0
	v_add_u32_e32 v4, s40, v221
	ds_read_b64_tr_b16 v[168:169], v4 offset:24576
	ds_read_b64_tr_b16 v[170:171], v4 offset:25088
	s_waitcnt lgkmcnt(9)
	v_mfma_f32_32x32x16_bf16 v[80:95], v[64:67], v[148:151], v[48:63]
	v_add_f32_e32 v2, v112, v113
	v_add_f32_e32 v2, v114, v2
	v_add_f32_e32 v2, v115, v2
	v_add_f32_e32 v2, v116, v2
	v_add_f32_e32 v2, v117, v2
	v_cvt_pk_bf16_f32 v156, v112, v113
	v_cvt_pk_bf16_f32 v157, v114, v115
	ds_read_b64_tr_b16 v[164:165], v4 offset:28672
	ds_read_b64_tr_b16 v[166:167], v4 offset:29184
	s_waitcnt lgkmcnt(10)
	v_mfma_f32_32x32x16_bf16 v[64:79], v[160:163], v[148:151], v[48:63]
	v_add_f32_e32 v2, v118, v2
	v_add_f32_e32 v2, v119, v2
	v_add_f32_e32 v2, v120, v2
	v_add_f32_e32 v2, v121, v2
	v_cvt_pk_bf16_f32 v158, v116, v117
	v_cvt_pk_bf16_f32 v159, v118, v119
	ds_read_b64_tr_b16 v[160:161], v4 offset:25600
	ds_read_b64_tr_b16 v[162:163], v4 offset:26112
	s_waitcnt lgkmcnt(11)
	v_mfma_f32_32x32x16_bf16 v[80:95], v[192:195], v[140:143], v[80:95]
	v_add_f32_e32 v2, v122, v2
	v_add_f32_e32 v2, v123, v2
	v_add_f32_e32 v2, v124, v2
	v_add_f32_e32 v2, v125, v2
	v_cvt_pk_bf16_f32 v152, v120, v121
	v_cvt_pk_bf16_f32 v153, v122, v123
	ds_read_b64_tr_b16 v[116:117], v4 offset:29696
	ds_read_b64_tr_b16 v[118:119], v4 offset:30208
	s_waitcnt lgkmcnt(12)
	v_mfma_f32_32x32x16_bf16 v[64:79], v[184:187], v[140:143], v[64:79]
	v_add_f32_e32 v2, v126, v2
	v_add_f32_e32 v2, v127, v2
	v_add_f32_e32 v2, v96, v2
	v_add_f32_e32 v2, v97, v2
	v_cvt_pk_bf16_f32 v154, v124, v125
	v_cvt_pk_bf16_f32 v155, v126, v127
	ds_read_b64_tr_b16 v[112:113], v4 offset:26624
	ds_read_b64_tr_b16 v[114:115], v4 offset:27136
	s_waitcnt lgkmcnt(13)
	v_mfma_f32_32x32x16_bf16 v[80:95], v[188:191], v[132:135], v[80:95]
	v_add_f32_e32 v2, v98, v2
	v_add_f32_e32 v2, v99, v2
	v_add_f32_e32 v2, v100, v2
	v_add_f32_e32 v2, v101, v2
	v_cvt_pk_bf16_f32 v144, v96, v97
	v_cvt_pk_bf16_f32 v145, v98, v99
	ds_read_b64_tr_b16 v[10:11], v4 offset:30720
	ds_read_b64_tr_b16 v[12:13], v4 offset:31232
	s_waitcnt lgkmcnt(14)
	v_mfma_f32_32x32x16_bf16 v[64:79], v[176:179], v[132:135], v[64:79]
	v_add_f32_e32 v2, v102, v2
	v_add_f32_e32 v2, v103, v2
	v_add_f32_e32 v2, v104, v2
	v_add_f32_e32 v2, v105, v2
	v_cvt_pk_bf16_f32 v146, v100, v101
	v_cvt_pk_bf16_f32 v147, v102, v103
	ds_read_b64_tr_b16 v[6:7], v4 offset:27648
	ds_read_b64_tr_b16 v[8:9], v4 offset:28160
	s_waitcnt lgkmcnt(14)
	v_mfma_f32_32x32x16_bf16 v[80:95], v[180:183], v[128:131], v[80:95]
	v_add_f32_e32 v2, v106, v2
	v_add_f32_e32 v2, v107, v2
	v_add_f32_e32 v2, v108, v2
	v_add_f32_e32 v15, v109, v2
	v_cvt_pk_bf16_f32 v136, v104, v105
	v_cvt_pk_bf16_f32 v137, v106, v107
	ds_read_b64_tr_b16 v[2:3], v4 offset:31744
	ds_read_b64_tr_b16 v[4:5], v4 offset:32256
	v_mfma_f32_32x32x16_bf16 v[64:79], v[172:175], v[128:131], v[64:79]
	v_add_f32_e32 v15, v110, v15
	v_add_f32_e32 v15, v111, v15
	v_add_f32_e32 v15, 0, v15
	v_cvt_pk_bf16_f32 v138, v108, v109
	v_cvt_pk_bf16_f32 v139, v110, v111
	s_waitcnt lgkmcnt(14)
	v_mfma_f32_32x32x16_bf16 v[32:47], v[156:159], v[168:171], v[32:47]
	v_max_f32_e32 v96, v81, v81
	v_max_f32_e32 v97, v80, v80
	v_max_f32_e32 v96, v97, v96
	s_nop 3
	v_max3_f32 v97, v82, v83, v65
	v_max3_f32 v96, v96, v64, v66
	v_max3_f32 v96, v96, v67, v84
	v_max3_f32 v97, v97, v86, v87
	v_max3_f32 v96, v96, v85, v68
	s_waitcnt lgkmcnt(12)
	v_mfma_f32_32x32x16_bf16 v[16:31], v[156:159], v[164:167], v[16:31]
	v_max3_f32 v97, v97, v70, v71
	v_max3_f32 v96, v96, v69, v88
	v_max3_f32 v97, v97, v90, v91
	v_max3_f32 v96, v96, v89, v72
	v_max3_f32 v97, v97, v74, v75
	v_max3_f32 v96, v96, v73, v92
	v_max3_f32 v97, v97, v94, v95
	v_max3_f32 v96, v96, v93, v76
	v_max3_f32 v97, v97, v78, v79
	v_add_f32_e32 v223, v14, v15
	v_max3_f32 v14, v96, v77, v97
	v_mov_b32_e32 v15, v14
	s_nop 1
	v_permlane32_swap_b32_e32 v14, v15
	s_add_i32 s8, s38, s46
	s_mov_b32 s9, m0
	s_mov_b32 m0, s8
	s_nop 0
	global_load_lds_dwordx4 v[202:203], off
	s_mov_b32 m0, s9
	v_max_f32_e32 v14, v14, v15
	s_add_i32 s8, s13, s47
	s_mov_b32 s9, m0
	s_mov_b32 m0, s8
	s_nop 0
	global_load_lds_dwordx4 v[200:201], off
	s_mov_b32 m0, s9
	v_cmp_lt_f32_e32 vcc, s53, v14
	s_cmp_lg_u64 vcc, 0
	s_cselect_b64 s[8:9], -1, 0
	s_cbranch_vccnz .LBB0_1558
.LBB0_1551:
	v_exp_f32_e32 v80, v80
	v_exp_f32_e32 v81, v81
	v_exp_f32_e32 v82, v82
	v_exp_f32_e32 v83, v83
	v_exp_f32_e32 v84, v84
	v_exp_f32_e32 v85, v85
	v_exp_f32_e32 v86, v86
	v_exp_f32_e32 v87, v87
	v_add_u32_e32 v14, s13, v220
	ds_read_b128 v[188:191], v14
	ds_read_b128 v[184:187], v14 offset:512
	s_waitcnt lgkmcnt(12)
	v_mfma_f32_32x32x16_bf16 v[32:47], v[152:155], v[160:163], v[32:47]
	v_exp_f32_e32 v88, v88
	v_exp_f32_e32 v89, v89
	v_exp_f32_e32 v90, v90
	v_exp_f32_e32 v91, v91
	ds_read_b128 v[180:183], v14 offset:2048
	ds_read_b128 v[176:179], v14 offset:2560
	s_waitcnt lgkmcnt(12)
	v_mfma_f32_32x32x16_bf16 v[16:31], v[152:155], v[116:119], v[16:31]
	v_exp_f32_e32 v92, v92
	v_exp_f32_e32 v93, v93
	v_exp_f32_e32 v94, v94
	v_exp_f32_e32 v95, v95
	ds_read_b128 v[172:175], v14 offset:4096
	ds_read_b128 v[168:171], v14 offset:4608
	s_waitcnt lgkmcnt(12)
	v_mfma_f32_32x32x16_bf16 v[32:47], v[144:147], v[112:115], v[32:47]
	v_exp_f32_e32 v64, v64
	v_exp_f32_e32 v65, v65
	v_exp_f32_e32 v66, v66
	v_exp_f32_e32 v67, v67
	ds_read_b128 v[164:167], v14 offset:6144
	ds_read_b128 v[160:163], v14 offset:6656
	s_waitcnt lgkmcnt(12)
	v_mfma_f32_32x32x16_bf16 v[16:31], v[144:147], v[10:13], v[16:31]
	v_exp_f32_e32 v68, v68
	v_exp_f32_e32 v69, v69
	v_exp_f32_e32 v70, v70
	v_exp_f32_e32 v71, v71
	s_waitcnt lgkmcnt(10)
	v_mfma_f32_32x32x16_bf16 v[32:47], v[136:139], v[6:9], v[32:47]
	v_exp_f32_e32 v72, v72
	v_exp_f32_e32 v73, v73
	v_exp_f32_e32 v74, v74
	v_exp_f32_e32 v75, v75
	s_waitcnt lgkmcnt(8)
	v_mfma_f32_32x32x16_bf16 v[16:31], v[136:139], v[2:5], v[16:31]
	v_exp_f32_e32 v76, v76
	v_exp_f32_e32 v77, v77
	v_exp_f32_e32 v78, v78
	v_exp_f32_e32 v79, v79
	s_waitcnt vmcnt(2) lgkmcnt(0)
	s_barrier
	s_andn2_b64 vcc, exec, s[8:9]
	s_cbranch_vccnz .LBB0_1553
	s_waitcnt lgkmcnt(0)
	ds_read_b128 v[2:5], v0 offset:49248
	ds_read_b128 v[6:9], v0 offset:49216
	ds_read_b128 v[10:13], v0 offset:49184
	ds_read_b128 v[96:99], v0 offset:49152
	s_waitcnt lgkmcnt(3)
	v_pk_mul_f32 v[44:45], v[44:45], v[2:3]
	s_waitcnt lgkmcnt(2)
	v_pk_mul_f32 v[40:41], v[40:41], v[6:7]
	s_waitcnt lgkmcnt(1)
	v_pk_mul_f32 v[36:37], v[36:37], v[10:11]
	v_pk_mul_f32 v[46:47], v[46:47], v[4:5]
	v_pk_mul_f32 v[42:43], v[42:43], v[8:9]
	v_pk_mul_f32 v[38:39], v[38:39], v[12:13]
	s_waitcnt lgkmcnt(0)
	v_pk_mul_f32 v[34:35], v[34:35], v[98:99]
	v_pk_mul_f32 v[32:33], v[32:33], v[96:97]
	v_pk_mul_f32 v[28:29], v[28:29], v[2:3]
	v_pk_mul_f32 v[24:25], v[24:25], v[6:7]
	v_pk_mul_f32 v[20:21], v[20:21], v[10:11]
	v_pk_mul_f32 v[30:31], v[30:31], v[4:5]
	v_pk_mul_f32 v[26:27], v[26:27], v[8:9]
	v_pk_mul_f32 v[22:23], v[22:23], v[12:13]
	v_pk_mul_f32 v[18:19], v[18:19], v[98:99]
	v_pk_mul_f32 v[16:17], v[16:17], v[96:97]
